# weight conversion split: w_in stays in the norm phase, the other five matrices are converted during the in-proj GEMM by the 192 workgroups whose third tile slot is padding
# speedup vs baseline: 1.0158x; 1.0063x over previous
.Lg256b_ip_done:
	s_and_b32 s3, s79, 7
	s_cmp_lt_u32 s3, 5
	s_cbranch_scc1 .Lip_conv_ret
	s_sub_u32 s3, s3, 5
	s_bfe_u32 s4, s79, 0x30003
	s_mul_i32 s4, s4, 3
	s_add_u32 s3, s3, s4
	s_lshl_b32 s3, s3, 3
	s_add_u32 s3, s3, s65
	s_add_u32 s24, s3, 0xa90
	s_load_dwordx2 s[6:7], s[0:1], 0x130
	s_branch .Lip_conv

.LBB0_853:
	s_load_dwordx2 s[6:7], s[0:1], 0x130
	s_waitcnt lgkmcnt(0)
	v_mov_b32_e32 v2, v133
	v_lshrrev_b32_e32 v3, 4, v2
	v_and_b32_e32 v4, 15, v2
	v_lshlrev_b32_e32 v4, 2, v4
	v_mul_u32_u24_e32 v5, 65, v3
	v_add_lshl_u32 v5, v5, v4, 2
	v_and_b32_e32 v7, 63, v2
	v_lshrrev_b32_e32 v27, 6, v2
	v_and_b32_e32 v24, 15, v7
	v_lshrrev_b32_e32 v25, 4, v7
	v_readfirstlane_b32 s22, v27
	v_mul_u32_u24_e32 v6, 520, v25
	v_lshl_add_u32 v6, v27, 4, v6
	v_add_lshl_u32 v6, v6, v24, 2
	v_lshlrev_b32_e32 v26, 4, v7
	s_sub_u32 s14, s24, 2048
	s_mov_b32 s25, s14
	s_cmp_ge_u32 s25, 656
	s_cbranch_scc1 .Lcp_dec_zero_f
	s_cmp_lt_u32 s25, 656
	s_cbranch_scc1 .Lcp_dec_win_f
	s_cmp_lt_u32 s25, 1680
	s_cbranch_scc1 .Lcp_dec_wm_f
	s_cmp_lt_u32 s25, 1936
	s_cbranch_scc1 .Lcp_dec_wb_f
	s_cmp_lt_u32 s25, 2192
	s_cbranch_scc1 .Lcp_dec_wout_f
	s_cmp_lt_u32 s25, 3216
	s_cbranch_scc1 .Lcp_dec_w1_f
	s_cmp_lt_u32 s25, 4240
	s_cbranch_scc1 .Lcp_dec_w2_f
	s_branch .Lcp_dec_zero_f

.Lcp_dec_done_f:
.Lcp_loop:
	s_add_u32 s15, s24, s42
	s_mov_b32 s12, 5
	s_mov_b32 s16, 0
	s_cmp_gt_u32 s15, 0xa90
	s_cbranch_scc1 .Lcp_noA
	s_sub_u32 s14, s15, 2048
	s_mov_b32 s25, s14
	s_cmp_ge_u32 s25, 656
	s_cbranch_scc1 .Lcp_dec_zero_a
	s_cmp_lt_u32 s25, 656
	s_cbranch_scc1 .Lcp_dec_win_a
	s_cmp_lt_u32 s25, 1680
	s_cbranch_scc1 .Lcp_dec_wm_a
	s_cmp_lt_u32 s25, 1936
	s_cbranch_scc1 .Lcp_dec_wb_a
	s_cmp_lt_u32 s25, 2192
	s_cbranch_scc1 .Lcp_dec_wout_a
	s_cmp_lt_u32 s25, 3216
	s_cbranch_scc1 .Lcp_dec_w1_a
	s_cmp_lt_u32 s25, 4240
	s_cbranch_scc1 .Lcp_dec_w2_a
	s_branch .Lcp_dec_zero_a

.Lcp_pdone_a:
	s_cmp_eq_u32 s12, 5
	s_cbranch_scc1 .Lcp_exit
	s_mov_b32 s24, s15
	s_add_u32 s15, s24, s42
	s_mov_b32 s9, 5
	s_mov_b32 s16, 0
	s_cmp_gt_u32 s15, 0xa90
	s_cbranch_scc1 .Lcp_noB
	s_sub_u32 s14, s15, 2048
	s_mov_b32 s25, s14
	s_cmp_ge_u32 s25, 656
	s_cbranch_scc1 .Lcp_dec_zero_b
	s_cmp_lt_u32 s25, 656
	s_cbranch_scc1 .Lcp_dec_win_b
	s_cmp_lt_u32 s25, 1680
	s_cbranch_scc1 .Lcp_dec_wm_b
	s_cmp_lt_u32 s25, 1936
	s_cbranch_scc1 .Lcp_dec_wb_b
	s_cmp_lt_u32 s25, 2192
	s_cbranch_scc1 .Lcp_dec_wout_b
	s_cmp_lt_u32 s25, 3216
	s_cbranch_scc1 .Lcp_dec_w1_b
	s_cmp_lt_u32 s25, 4240
	s_cbranch_scc1 .Lcp_dec_w2_b
	s_branch .Lcp_dec_zero_b

.Lip_conv:
	s_waitcnt lgkmcnt(0)
	v_mov_b32_e32 v2, v133
	v_lshrrev_b32_e32 v3, 4, v2
	v_and_b32_e32 v4, 15, v2
	v_lshlrev_b32_e32 v4, 2, v4
	v_mul_u32_u24_e32 v5, 65, v3
	v_add_lshl_u32 v5, v5, v4, 2
	v_and_b32_e32 v7, 63, v2
	v_lshrrev_b32_e32 v27, 6, v2
	v_and_b32_e32 v24, 15, v7
	v_lshrrev_b32_e32 v25, 4, v7
	v_readfirstlane_b32 s22, v27
	v_mul_u32_u24_e32 v6, 520, v25
	v_lshl_add_u32 v6, v27, 4, v6
	v_add_lshl_u32 v6, v6, v24, 2
	v_lshlrev_b32_e32 v26, 4, v7
	s_sub_u32 s14, s24, 2048
	s_mov_b32 s25, s14
	s_cmp_ge_u32 s25, 4240
	s_cbranch_scc1 .Lcq_dec_zero_f
	s_cmp_lt_u32 s25, 656
	s_cbranch_scc1 .Lcq_dec_win_f
	s_cmp_lt_u32 s25, 1680
	s_cbranch_scc1 .Lcq_dec_wm_f
	s_cmp_lt_u32 s25, 1936
	s_cbranch_scc1 .Lcq_dec_wb_f
	s_cmp_lt_u32 s25, 2192
	s_cbranch_scc1 .Lcq_dec_wout_f
	s_cmp_lt_u32 s25, 3216
	s_cbranch_scc1 .Lcq_dec_w1_f
	s_cmp_lt_u32 s25, 4240
	s_cbranch_scc1 .Lcq_dec_w2_f
	s_branch .Lcq_dec_zero_f

.Lcq_dec_done_f:
.Lcq_loop:
	s_add_u32 s15, s24, 192
	s_mov_b32 s12, 5
	s_mov_b32 s16, 0
	s_cmp_gt_u32 s15, 0x188f
	s_cbranch_scc1 .Lcq_noA
	s_sub_u32 s14, s15, 2048
	s_mov_b32 s25, s14
	s_cmp_ge_u32 s25, 4240
	s_cbranch_scc1 .Lcq_dec_zero_a
	s_cmp_lt_u32 s25, 656
	s_cbranch_scc1 .Lcq_dec_win_a
	s_cmp_lt_u32 s25, 1680
	s_cbranch_scc1 .Lcq_dec_wm_a
	s_cmp_lt_u32 s25, 1936
	s_cbranch_scc1 .Lcq_dec_wb_a
	s_cmp_lt_u32 s25, 2192
	s_cbranch_scc1 .Lcq_dec_wout_a
	s_cmp_lt_u32 s25, 3216
	s_cbranch_scc1 .Lcq_dec_w1_a
	s_cmp_lt_u32 s25, 4240
	s_cbranch_scc1 .Lcq_dec_w2_a
	s_branch .Lcq_dec_zero_a

.Lcq_pdone_a:
	s_cmp_eq_u32 s12, 5
	s_cbranch_scc1 .Lcq_exit
	s_mov_b32 s24, s15
	s_add_u32 s15, s24, 192
	s_mov_b32 s9, 5
	s_mov_b32 s16, 0
	s_cmp_gt_u32 s15, 0x188f
	s_cbranch_scc1 .Lcq_noB
	s_sub_u32 s14, s15, 2048
	s_mov_b32 s25, s14
	s_cmp_ge_u32 s25, 4240
	s_cbranch_scc1 .Lcq_dec_zero_b
	s_cmp_lt_u32 s25, 656
	s_cbranch_scc1 .Lcq_dec_win_b
	s_cmp_lt_u32 s25, 1680
	s_cbranch_scc1 .Lcq_dec_wm_b
	s_cmp_lt_u32 s25, 1936
	s_cbranch_scc1 .Lcq_dec_wb_b
	s_cmp_lt_u32 s25, 2192
	s_cbranch_scc1 .Lcq_dec_wout_b
	s_cmp_lt_u32 s25, 3216
	s_cbranch_scc1 .Lcq_dec_w1_b
	s_cmp_lt_u32 s25, 4240
	s_cbranch_scc1 .Lcq_dec_w2_b
	s_branch .Lcq_dec_zero_b
